# P1 GEMM: k-step k in LDS stage (k+2)&3; the next tile's k-steps 0,1 are requested during the current tile's last k-step (stages 2/3, untouched by the epilogue staging), its header requests only k-step
# speedup vs baseline: 1.0237x; 1.0010x over previous
.LBB0_157:
	v_writelane_b32 v248, s36, 4
	s_nop 1
	v_writelane_b32 v248, s37, 5
	s_or_b64 exec, exec, s[0:1]
	s_add_u32 s28, s84, 0x1b00000
	s_addc_u32 s29, s85, 0
	s_lshl_b32 s0, s2, 4
	s_and_b32 s4, s86, 7
	s_lshr_b32 s6, s2, 3
	s_and_b32 s7, s0, 0x70
	s_add_u32 s0, s84, 0xeb00000
	s_addc_u32 s1, s85, 0
	s_add_u32 s42, s84, 0xcb00000
	s_addc_u32 s43, s85, 0
	s_add_u32 s44, s84, 0x13b00000
	s_addc_u32 s45, s85, 0
	s_add_u32 s30, s84, 0xdb00000
	s_addc_u32 s31, s85, 0
	s_add_u32 s46, s84, 0xbb00000
	s_addc_u32 s47, s85, 0
	s_add_u32 s10, s84, 0x5b00000
	s_addc_u32 s11, s85, 0
	s_lshr_b32 s14, s86, 3
	s_cmp_eq_u32 s4, 0
	s_cselect_b64 s[38:39], -1, 0
	s_and_b64 s[4:5], s[38:39], exec
	s_movk_i32 s4, 0xf0
	s_cselect_b32 s57, s6, s2
	s_cselect_b32 s27, s4, 0x780
	s_movk_i32 s21, 0x70
	s_cselect_b32 s56, s7, 0
	s_cselect_b32 s50, s14, s86
	s_cmp_lt_i32 s57, s27
	v_mov_b32_e32 v0, v191
	s_waitcnt lgkmcnt(0)
	s_barrier
	s_cbranch_scc0 .LBB0_248
	v_ashrrev_i32_e32 v1, 6, v0
	v_and_b32_e32 v4, 1, v1
	v_bfe_u32 v2, v0, 2, 4
	v_lshrrev_b32_e32 v5, 4, v0
	v_and_b32_e32 v7, 31, v0
	v_lshl_or_b32 v179, v1, 4, v2
	v_xor_b32_e32 v2, v5, v0
	v_lshlrev_b32_e32 v9, 6, v7
	v_lshlrev_b32_e32 v132, 7, v4
	v_lshlrev_b32_e32 v2, 3, v2
	v_lshl_or_b32 v184, v4, 13, v9
	v_or_b32_e32 v4, v132, v7
	v_ashrrev_i32_e32 v3, 7, v0
	v_and_b32_e32 v2, 24, v2
	v_lshlrev_b32_e32 v185, 6, v4
	s_add_i32 s4, 16, 0x1c000
	v_and_b32_e32 v133, 63, v0
	v_mov_b32_e32 v129, 0
	v_lshlrev_b32_e32 v128, 1, v2
	v_bfe_u32 v8, v0, 5, 1
	v_lshl_or_b32 v182, v3, 12, v9
	v_lshrrev_b32_e32 v10, 2, v0
	v_bfe_u32 v11, v0, 2, 2
	v_add_u32_e32 v187, s4, v185
	v_add_u32_e32 v188, s4, v184
	s_add_i32 s4, 16, 0x18000
	v_bitop3_b32 v0, v5, 3, v0 bitop3:0x48
	v_lshl_add_u64 v[130:131], s[84:85], 0, v[128:129]
	v_add_u32_e32 v189, s4, v182
	s_add_i32 s4, 16, 0x14000
	v_lshlrev_b32_e32 v128, 4, v0
	v_lshlrev_b32_e32 v6, 10, v1
	v_lshl_add_u32 v192, v1, 13, 16
	v_add_u32_e32 v193, s4, v185
	v_add_u32_e32 v194, s4, v184
	s_add_i32 s6, 16, 0x10000
	v_lshl_add_u64 v[0:1], s[84:85], 0, v[128:129]
	s_mov_b64 s[4:5], 0xc0
	v_add_u32_e32 v181, 16, v6
	v_bitop3_b32 v10, v10, v8, 3 bitop3:0x6c
	v_bitop3_b32 v4, v8, v11, 2 bitop3:0x36
	v_lshl_add_u64 v[134:135], v[0:1], 0, s[4:5]
	s_mov_b64 s[4:5], 0x1b000c0
	v_add_u32_e32 v206, s6, v6
	v_add_u32_e32 v180, 0x80, v179
	v_lshlrev_b32_e32 v183, 4, v10
	v_lshlrev_b32_e32 v186, 4, v4
	v_lshlrev_b32_e32 v190, 6, v3
	v_add_u32_e32 v195, s6, v182
	v_add_u32_e32 v196, 16, v182
	v_add_u32_e32 v197, 16, v184
	v_add_u32_e32 v198, 16, v185
	v_lshl_add_u64 v[136:137], v[0:1], 0, s[4:5]
	v_lshlrev_b32_e32 v138, 1, v2
	v_mov_b32_e32 v139, v129
	s_movk_i32 s51, 0x2000
	v_add_u32_e32 v199, 0x2000, v181
	v_add_u32_e32 v200, 0x4000, v181
	v_add_u32_e32 v201, 0x6000, v181
	s_mov_b64 s[14:15], 0x1b00040
	v_add_u32_e32 v202, 0x8000, v181
	v_add_u32_e32 v203, 0xa000, v181
	v_add_u32_e32 v204, 0xc000, v181
	v_add_u32_e32 v205, 0xe000, v181
	s_mov_b64 s[16:17], 0x1b00080
	s_mov_b64 s[18:19], 0x80
	s_movk_i32 s55, 0x3ff
	s_movk_i32 s72, 0xc0
	s_mov_b32 s73, 0x3ffff900
	s_movk_i32 s74, 0xff
	s_mov_b32 s75, 0x1fffffc0
	s_movk_i32 s76, 0x50
	s_movk_i32 s77, 0x60
	s_mov_b32 s78, 0xfffffc0
	s_mov_b32 s79, 0x9b00000
	s_movk_i32 s82, 0xfa00
	s_movk_i32 s83, 0x1000
	s_movk_i32 s90, 0x3000
	s_mov_b32 s91, 0x1fffff80
	s_mov_b32 s20, 0x3e38aa3b
	v_add_u32_e32 v207, 0x2000, v206
	v_add_u32_e32 v208, 0x4000, v206
	v_add_u32_e32 v209, 0x6000, v206
	s_mov_b32 s92, s57
	s_mov_b32 s5, 0
	s_nop 0
	v_writelane_b32 v255, s5, 0
	s_branch .LBB0_160

.LBB0_160:
	v_readlane_b32 s5, v255, 0
	s_cmp_lg_u32 s5, 0
	s_cselect_b64 vcc, -1, 0
	s_mul_hi_i32 s4, s92, 0x88888889
	s_add_i32 s4, s4, s92
	s_lshr_b32 s5, s4, 31
	s_ashr_i32 s4, s4, 3
	s_add_i32 s4, s4, s5
	s_add_i32 s5, s4, s56
	s_mul_i32 s6, s4, 15
	s_sub_i32 s94, s92, s6
	s_lshl_b32 s6, s5, 8
	v_add_u32_e32 v4, s6, v179
	v_ashrrev_i32_e32 v5, 31, v4
	v_lshlrev_b64 v[4:5], 11, v[4:5]
	v_lshl_add_u64 v[6:7], s[28:29], 0, v[4:5]
	v_readfirstlane_b32 s5, v206
	v_lshl_add_u64 v[6:7], v[6:7], 0, v[138:139]
	s_mov_b32 m0, s5
	s_barrier
	s_cbranch_vccnz .Lgc161_s0
	global_load_lds_dwordx4 v[6:7], off
.Lgc161_s0:
	v_add_u32_e32 v6, s6, v180
	s_lshl_b32 s93, s94, 8
	v_ashrrev_i32_e32 v7, 31, v6
	v_add_u32_e32 v0, s93, v179
	v_lshlrev_b64 v[6:7], 11, v[6:7]
	v_ashrrev_i32_e32 v1, 31, v0
	v_add_u32_e32 v2, s93, v180
	v_lshl_add_u64 v[8:9], s[28:29], 0, v[6:7]
	v_readfirstlane_b32 s5, v207
	v_lshlrev_b64 v[0:1], 11, v[0:1]
	v_ashrrev_i32_e32 v3, 31, v2
	v_lshl_add_u64 v[8:9], v[8:9], 0, v[138:139]
	s_mov_b32 m0, s5
	v_readfirstlane_b32 s5, v208
	v_lshl_add_u64 v[0:1], v[130:131], 0, v[0:1]
	v_lshlrev_b64 v[2:3], 11, v[2:3]
	s_cbranch_vccnz .Lgc161_s1
	global_load_lds_dwordx4 v[8:9], off
.Lgc161_s1:
	s_mov_b32 m0, s5
	v_readfirstlane_b32 s5, v209
	v_lshl_add_u64 v[2:3], v[130:131], 0, v[2:3]
	s_cbranch_vccnz .Lgc161_s2
	global_load_lds_dwordx4 v[0:1], off
.Lgc161_s2:
	s_mov_b32 m0, s5
	v_lshl_add_u64 v[8:9], v[130:131], 0, v[4:5]
	v_readfirstlane_b32 s5, v202
	s_cbranch_vccnz .Lgc161_s3
	global_load_lds_dwordx4 v[2:3], off
.Lgc161_s3:
	v_lshl_add_u64 v[10:11], v[8:9], 0, s[14:15]
	s_add_i32 m0, s5, 0x10000
	v_readfirstlane_b32 s5, v203
	s_cbranch_vccnz .Lgc161_s4
	global_load_lds_dwordx4 v[10:11], off
.Lgc161_s4:
	v_lshl_add_u64 v[10:11], v[130:131], 0, v[6:7]
	v_lshl_add_u64 v[12:13], v[10:11], 0, s[14:15]
	s_add_i32 m0, s5, 0x10000
	v_readfirstlane_b32 s5, v204
	s_cbranch_vccnz .Lgc161_s5
	global_load_lds_dwordx4 v[12:13], off
.Lgc161_s5:
	v_lshl_add_u64 v[12:13], v[0:1], 0, 64
	s_add_i32 m0, s5, 0x10000
	v_readfirstlane_b32 s5, v205
	s_cbranch_vccnz .Lgc161_s6
	global_load_lds_dwordx4 v[12:13], off
.Lgc161_s6:
	v_lshl_add_u64 v[12:13], v[2:3], 0, 64
	s_add_i32 m0, s5, 0x10000
	v_readfirstlane_b32 s5, v181
	s_cbranch_vccnz .Lgc161_s7
	global_load_lds_dwordx4 v[12:13], off
.Lgc161_s7:
	v_lshl_add_u64 v[8:9], v[8:9], 0, s[16:17]
	s_mov_b32 m0, s5
	v_readfirstlane_b32 s5, v199
	global_load_lds_dwordx4 v[8:9], off
	v_lshl_add_u64 v[8:9], v[10:11], 0, s[16:17]
	s_mov_b32 m0, s5
	v_readfirstlane_b32 s5, v200
	global_load_lds_dwordx4 v[8:9], off
	v_lshl_add_u64 v[0:1], v[0:1], 0, s[18:19]
	s_mov_b32 m0, s5
	v_readfirstlane_b32 s5, v201
	global_load_lds_dwordx4 v[0:1], off
	v_lshl_add_u64 v[0:1], v[2:3], 0, s[18:19]
	s_mov_b32 m0, s5
	s_lshl_b32 s5, s92, 8
	global_load_lds_dwordx4 v[0:1], off
	v_add_u32_e32 v0, s5, v179
	s_mulk_i32 s4, 0xf00
	v_subrev_u32_e32 v0, s4, v0
	v_ashrrev_i32_e32 v1, 31, v0
	v_lshlrev_b64 v[0:1], 11, v[0:1]
	v_lshl_add_u64 v[140:141], v[134:135], 0, v[0:1]
	v_add_u32_e32 v0, s5, v180
	v_subrev_u32_e32 v0, s4, v0
	v_ashrrev_i32_e32 v1, 31, v0
	v_lshlrev_b64 v[0:1], 11, v[0:1]
	v_lshl_add_u64 v[142:143], v[134:135], 0, v[0:1]
	v_lshl_add_u64 v[144:145], v[136:137], 0, v[4:5]
	v_lshl_add_u64 v[146:147], v[136:137], 0, v[6:7]
	s_mov_b64 s[4:5], 0
	s_mov_b32 s7, 0x28000
	v_mov_b32_e32 v0, 0
	v_mov_b32_e32 v1, v129
	v_mov_b32_e32 v2, v129
	v_mov_b32_e32 v3, v129
	v_mov_b32_e32 v4, v129
	v_mov_b32_e32 v5, v129
	v_mov_b32_e32 v6, v129
	v_mov_b32_e32 v7, v129
	v_mov_b32_e32 v8, v129
	v_mov_b32_e32 v9, v129
	v_mov_b32_e32 v10, v129
	v_mov_b32_e32 v11, v129
	v_mov_b32_e32 v12, v129
	v_mov_b32_e32 v13, v129
	v_mov_b32_e32 v14, v129
	v_mov_b32_e32 v15, v129
	v_mov_b32_e32 v16, 0
	v_mov_b32_e32 v17, v129
	v_mov_b32_e32 v18, v129
	v_mov_b32_e32 v19, v129
	v_mov_b32_e32 v20, v129
	v_mov_b32_e32 v21, v129
	v_mov_b32_e32 v22, v129
	v_mov_b32_e32 v23, v129
	v_mov_b32_e32 v24, v129
	v_mov_b32_e32 v25, v129
	v_mov_b32_e32 v26, v129
	v_mov_b32_e32 v27, v129
	v_mov_b32_e32 v28, v129
	v_mov_b32_e32 v29, v129
	v_mov_b32_e32 v30, v129
	v_mov_b32_e32 v31, v129
	v_mov_b32_e32 v64, 0
	v_mov_b32_e32 v65, v129
	v_mov_b32_e32 v66, v129
	v_mov_b32_e32 v67, v129
	v_mov_b32_e32 v68, v129
	v_mov_b32_e32 v69, v129
	v_mov_b32_e32 v70, v129
	v_mov_b32_e32 v71, v129
	v_mov_b32_e32 v72, v129
	v_mov_b32_e32 v73, v129
	v_mov_b32_e32 v74, v129
	v_mov_b32_e32 v75, v129
	v_mov_b32_e32 v76, v129
	v_mov_b32_e32 v77, v129
	v_mov_b32_e32 v78, v129
	v_mov_b32_e32 v79, v129
	v_mov_b32_e32 v80, 0
	v_mov_b32_e32 v81, v129
	v_mov_b32_e32 v82, v129
	v_mov_b32_e32 v83, v129
	v_mov_b32_e32 v84, v129
	v_mov_b32_e32 v85, v129
	v_mov_b32_e32 v86, v129
	v_mov_b32_e32 v87, v129
	v_mov_b32_e32 v88, v129
	v_mov_b32_e32 v89, v129
	v_mov_b32_e32 v90, v129
	v_mov_b32_e32 v91, v129
	v_mov_b32_e32 v92, v129
	v_mov_b32_e32 v93, v129
	v_mov_b32_e32 v94, v129
	v_mov_b32_e32 v95, v129
	v_mov_b32_e32 v32, 0
	v_mov_b32_e32 v33, v129
	v_mov_b32_e32 v34, v129
	v_mov_b32_e32 v35, v129
	v_mov_b32_e32 v36, v129
	v_mov_b32_e32 v37, v129
	v_mov_b32_e32 v38, v129
	v_mov_b32_e32 v39, v129
	v_mov_b32_e32 v40, v129
	v_mov_b32_e32 v41, v129
	v_mov_b32_e32 v42, v129
	v_mov_b32_e32 v43, v129
	v_mov_b32_e32 v44, v129
	v_mov_b32_e32 v45, v129
	v_mov_b32_e32 v46, v129
	v_mov_b32_e32 v47, v129
	v_mov_b32_e32 v48, 0
	v_mov_b32_e32 v49, v129
	v_mov_b32_e32 v50, v129
	v_mov_b32_e32 v51, v129
	v_mov_b32_e32 v52, v129
	v_mov_b32_e32 v53, v129
	v_mov_b32_e32 v54, v129
	v_mov_b32_e32 v55, v129
	v_mov_b32_e32 v56, v129
	v_mov_b32_e32 v57, v129
	v_mov_b32_e32 v58, v129
	v_mov_b32_e32 v59, v129
	v_mov_b32_e32 v60, v129
	v_mov_b32_e32 v61, v129
	v_mov_b32_e32 v62, v129
	v_mov_b32_e32 v63, v129
	v_mov_b32_e32 v96, 0
	v_mov_b32_e32 v97, v129
	v_mov_b32_e32 v98, v129
	v_mov_b32_e32 v99, v129
	v_mov_b32_e32 v100, v129
	v_mov_b32_e32 v101, v129
	v_mov_b32_e32 v102, v129
	v_mov_b32_e32 v103, v129
	v_mov_b32_e32 v104, v129
	v_mov_b32_e32 v105, v129
	v_mov_b32_e32 v106, v129
	v_mov_b32_e32 v107, v129
	v_mov_b32_e32 v108, v129
	v_mov_b32_e32 v109, v129
	v_mov_b32_e32 v110, v129
	v_mov_b32_e32 v111, v129
	v_mov_b32_e32 v112, 0
	v_mov_b32_e32 v113, v129
	v_mov_b32_e32 v114, v129
	v_mov_b32_e32 v115, v129
	v_mov_b32_e32 v116, v129
	v_mov_b32_e32 v117, v129
	v_mov_b32_e32 v118, v129
	v_mov_b32_e32 v119, v129
	v_readfirstlane_b32 s99, v181
	v_mov_b32_e32 v120, v129
	v_mov_b32_e32 v121, v129
	v_mov_b32_e32 v122, v129
	v_mov_b32_e32 v123, v129
	v_mov_b32_e32 v124, v129
	v_mov_b32_e32 v125, v129
	v_mov_b32_e32 v126, v129
	v_mov_b32_e32 v127, v129
.LBB0_161:
	s_add_i32 s22, s7, 0xfffe8000
	s_and_b32 s22, s22, 0x18000
	s_add_i32 s22, s22, 16
	v_add_u32_e32 v128, s22, v182
	v_add_u32_e32 v176, s22, v184
	v_add_u32_e32 v177, s22, v185
	v_add_u32_e32 v152, v128, v183
	v_add_u32_e32 v156, v176, v183
	v_add_u32_e32 v168, v177, v183
	v_add_u32_e32 v128, v128, v186
	s_and_b32 s98, s7, 0x18000
	s_add_i32 s98, s98, s99
	s_waitcnt vmcnt(8)
	s_waitcnt lgkmcnt(0)
	s_barrier
	ds_read_b128 v[148:151], v152
	ds_read_b128 v[152:155], v152 offset:2048
	ds_read_b128 v[156:159], v156 offset:16384
	ds_read_b128 v[160:163], v168 offset:18432
	ds_read_b128 v[164:167], v168 offset:20480
	ds_read_b128 v[168:171], v168 offset:22528
	ds_read_b128 v[172:175], v128
	ds_read_b128 v[210:213], v128 offset:2048
	v_add_u32_e32 v128, v176, v186
	v_add_u32_e32 v176, v177, v186
	ds_read_b128 v[214:217], v128 offset:16384
	ds_read_b128 v[218:221], v176 offset:18432
	ds_read_b128 v[222:225], v176 offset:20480
	ds_read_b128 v[226:229], v176 offset:22528
	v_lshl_add_u64 v[250:251], v[144:145], 0, s[4:5]
	s_mov_b32 m0, s98
	s_waitcnt lgkmcnt(9)
	v_mfma_f32_32x32x16_bf16 v[112:127], v[148:151], v[156:159], v[112:127]
	s_waitcnt lgkmcnt(8)
	v_mfma_f32_32x32x16_bf16 v[96:111], v[148:151], v[160:163], v[96:111]
	global_load_lds_dwordx4 v[250:251], off
	v_lshl_add_u64 v[250:251], v[146:147], 0, s[4:5]
	s_add_i32 m0, s98, 0x2000
	s_waitcnt lgkmcnt(7)
	v_mfma_f32_32x32x16_bf16 v[48:63], v[148:151], v[164:167], v[48:63]
	s_waitcnt lgkmcnt(6)
	v_mfma_f32_32x32x16_bf16 v[32:47], v[148:151], v[168:171], v[32:47]
	v_mfma_f32_32x32x16_bf16 v[80:95], v[152:155], v[156:159], v[80:95]
	v_mfma_f32_32x32x16_bf16 v[64:79], v[152:155], v[160:163], v[64:79]
	global_load_lds_dwordx4 v[250:251], off
	v_lshl_add_u64 v[250:251], v[140:141], 0, s[4:5]
	s_add_i32 m0, s98, 0x4000
	v_mfma_f32_32x32x16_bf16 v[16:31], v[152:155], v[164:167], v[16:31]
	v_mfma_f32_32x32x16_bf16 v[0:15], v[152:155], v[168:171], v[0:15]
	s_waitcnt lgkmcnt(3)
	v_mfma_f32_32x32x16_bf16 v[112:127], v[172:175], v[214:217], v[112:127]
	s_waitcnt lgkmcnt(2)
	v_mfma_f32_32x32x16_bf16 v[96:111], v[172:175], v[218:221], v[96:111]
	global_load_lds_dwordx4 v[250:251], off
	v_lshl_add_u64 v[250:251], v[142:143], 0, s[4:5]
	s_add_i32 m0, s98, 0x6000
	s_waitcnt lgkmcnt(1)
	v_mfma_f32_32x32x16_bf16 v[48:63], v[172:175], v[222:225], v[48:63]
	s_waitcnt lgkmcnt(0)
	v_mfma_f32_32x32x16_bf16 v[32:47], v[172:175], v[226:229], v[32:47]
	v_mfma_f32_32x32x16_bf16 v[80:95], v[210:213], v[214:217], v[80:95]
	v_mfma_f32_32x32x16_bf16 v[64:79], v[210:213], v[218:221], v[64:79]
	global_load_lds_dwordx4 v[250:251], off
	s_add_u32 s4, s4, 64
	s_addc_u32 s5, s5, 0
	s_add_i32 s7, s7, 0x8000
	s_cmpk_eq_i32 s4, 0x740
	v_mfma_f32_32x32x16_bf16 v[16:31], v[210:213], v[222:225], v[16:31]
	v_mfma_f32_32x32x16_bf16 v[0:15], v[210:213], v[226:229], v[0:15]
	s_cbranch_scc0 .LBB0_161
	s_waitcnt vmcnt(8)
	v_add_u32_e32 v128, v196, v183
	v_add_u32_e32 v128, 0x10000, v128
	s_waitcnt lgkmcnt(0)
	s_barrier
	ds_read_b128 v[140:143], v128 offset:32768
	ds_read_b128 v[144:147], v128 offset:34816
	v_add_u32_e32 v128, v197, v183
	v_add_u32_e32 v128, 0x10000, v128
	v_add_u32_e32 v160, v198, v183
	v_add_u32_e32 v160, 0x10000, v160
	ds_read_b128 v[148:151], v128 offset:49152
	ds_read_b128 v[152:155], v160 offset:51200
	ds_read_b128 v[156:159], v160 offset:53248
	ds_read_b128 v[160:163], v160 offset:55296
	v_add_u32_e32 v128, v196, v186
	v_add_u32_e32 v128, 0x10000, v128
	ds_read_b128 v[164:167], v128 offset:32768
	ds_read_b128 v[168:171], v128 offset:34816
	v_add_u32_e32 v128, v197, v186
	v_add_u32_e32 v128, 0x10000, v128
	v_add_u32_e32 v176, v198, v186
	v_add_u32_e32 v176, 0x10000, v176
	ds_read_b128 v[172:175], v128 offset:49152
	ds_read_b128 v[210:213], v176 offset:51200
	ds_read_b128 v[214:217], v176 offset:53248
	ds_read_b128 v[218:221], v176 offset:55296
	s_waitcnt lgkmcnt(0)
	v_mfma_f32_32x32x16_bf16 v[112:127], v[140:143], v[148:151], v[112:127]
	s_waitcnt vmcnt(4)
	v_add_u32_e32 v128, v193, v186
	v_add_u32_e32 v128, 0xffff0000, v128
	s_waitcnt lgkmcnt(0)
	s_barrier
	v_add_u32_e32 v176, v194, v183
	v_add_u32_e32 v176, 0xffff0000, v176
	v_mfma_f32_32x32x16_bf16 v[96:111], v[140:143], v[152:155], v[96:111]
	v_mfma_f32_32x32x16_bf16 v[48:63], v[140:143], v[156:159], v[48:63]
	v_mfma_f32_32x32x16_bf16 v[32:47], v[140:143], v[160:163], v[32:47]
	v_mfma_f32_32x32x16_bf16 v[80:95], v[144:147], v[148:151], v[80:95]
	v_mfma_f32_32x32x16_bf16 v[64:79], v[144:147], v[152:155], v[64:79]
	v_add_u32_e32 v152, v194, v186
	v_add_u32_e32 v152, 0xffff0000, v152
	v_mfma_f32_32x32x16_bf16 v[16:31], v[144:147], v[156:159], v[16:31]
	v_mfma_f32_32x32x16_bf16 v[0:15], v[144:147], v[160:163], v[0:15]
	ds_read_b128 v[140:143], v128 offset:4096
	ds_read_b128 v[144:147], v128 offset:2048
	ds_read_b128 v[148:151], v128 offset:6144
	ds_read_b128 v[152:155], v152
	v_add_u32_e32 v128, v195, v186
	v_add_u32_e32 v128, 0xffff0000, v128
	ds_read_b128 v[156:159], v128 offset:2048
	ds_read_b128 v[160:163], v128
	v_add_u32_e32 v128, v193, v183
	v_add_u32_e32 v128, 0xffff0000, v128
	v_mfma_f32_32x32x16_bf16 v[112:127], v[164:167], v[172:175], v[112:127]
	v_mfma_f32_32x32x16_bf16 v[96:111], v[164:167], v[210:213], v[96:111]
	v_mfma_f32_32x32x16_bf16 v[48:63], v[164:167], v[214:217], v[48:63]
	v_mfma_f32_32x32x16_bf16 v[32:47], v[164:167], v[218:221], v[32:47]
	v_mfma_f32_32x32x16_bf16 v[80:95], v[168:171], v[172:175], v[80:95]
	ds_read_b128 v[164:167], v128 offset:4096
	ds_read_b128 v[172:175], v128 offset:2048
	v_mfma_f32_32x32x16_bf16 v[64:79], v[168:171], v[210:213], v[64:79]
	v_mfma_f32_32x32x16_bf16 v[16:31], v[168:171], v[214:217], v[16:31]
	ds_read_b128 v[210:213], v128 offset:6144
	ds_read_b128 v[214:217], v176
	v_add_u32_e32 v128, v195, v183
	v_add_u32_e32 v128, 0xffff0000, v128
	ds_read_b128 v[222:225], v128 offset:2048
	ds_read_b128 v[226:229], v128
	v_mfma_f32_32x32x16_bf16 v[0:15], v[168:171], v[218:221], v[0:15]
	s_waitcnt lgkmcnt(0)
	v_mfma_f32_32x32x16_bf16 v[112:127], v[226:229], v[214:217], v[112:127]
	s_waitcnt vmcnt(0)
	v_add_u32_e32 v128, v187, v186
	v_add_u32_e32 v128, 0xffff0000, v128
	s_waitcnt lgkmcnt(0)
	s_barrier
	s_add_i32 s4, s92, s50
	s_cmp_ge_i32 s4, s27
	s_cselect_b32 s5, 0, 1
	v_writelane_b32 v255, s5, 0
	s_cbranch_scc1 .Lgc161_nopre
	s_mul_hi_i32 s7, s4, 0x88888889
	s_add_i32 s7, s7, s4
	s_lshr_b32 s22, s7, 31
	s_ashr_i32 s7, s7, 3
	s_add_i32 s7, s7, s22
	s_add_i32 s22, s7, s56
	s_mul_i32 s23, s7, 15
	s_sub_i32 s24, s4, s23
	s_lshl_b32 s23, s22, 8
	v_add_u32_e32 v234, s23, v179
	v_ashrrev_i32_e32 v235, 31, v234
	v_lshlrev_b64 v[234:235], 11, v[234:235]
	v_lshl_add_u64 v[236:237], s[28:29], 0, v[234:235]
	v_readfirstlane_b32 s22, v206
	v_lshl_add_u64 v[236:237], v[236:237], 0, v[138:139]
	s_mov_b32 m0, s22
	global_load_lds_dwordx4 v[236:237], off
	v_add_u32_e32 v236, s23, v180
	s_lshl_b32 s25, s24, 8
	v_ashrrev_i32_e32 v237, 31, v236
	v_add_u32_e32 v230, s25, v179
	v_lshlrev_b64 v[236:237], 11, v[236:237]
	v_ashrrev_i32_e32 v231, 31, v230
	v_add_u32_e32 v232, s25, v180
	v_lshl_add_u64 v[238:239], s[28:29], 0, v[236:237]
	v_readfirstlane_b32 s22, v207
	v_lshlrev_b64 v[230:231], 11, v[230:231]
	v_ashrrev_i32_e32 v233, 31, v232
	v_lshl_add_u64 v[238:239], v[238:239], 0, v[138:139]
	s_mov_b32 m0, s22
	v_readfirstlane_b32 s22, v208
	v_lshl_add_u64 v[230:231], v[130:131], 0, v[230:231]
	v_lshlrev_b64 v[232:233], 11, v[232:233]
	global_load_lds_dwordx4 v[238:239], off
	s_mov_b32 m0, s22
	v_readfirstlane_b32 s22, v209
	v_lshl_add_u64 v[232:233], v[130:131], 0, v[232:233]
	global_load_lds_dwordx4 v[230:231], off
	s_mov_b32 m0, s22
	v_lshl_add_u64 v[238:239], v[130:131], 0, v[234:235]
	v_readfirstlane_b32 s22, v202
	global_load_lds_dwordx4 v[232:233], off
	v_lshl_add_u64 v[240:241], v[238:239], 0, s[14:15]
	s_add_i32 m0, s22, 0x10000
	v_readfirstlane_b32 s22, v203
	global_load_lds_dwordx4 v[240:241], off
	v_lshl_add_u64 v[240:241], v[130:131], 0, v[236:237]
	v_lshl_add_u64 v[244:245], v[240:241], 0, s[14:15]
	s_add_i32 m0, s22, 0x10000
	v_readfirstlane_b32 s22, v204
	global_load_lds_dwordx4 v[244:245], off
	v_lshl_add_u64 v[244:245], v[230:231], 0, 64
	s_add_i32 m0, s22, 0x10000
	v_readfirstlane_b32 s22, v205
	global_load_lds_dwordx4 v[244:245], off
	v_lshl_add_u64 v[244:245], v[232:233], 0, 64
	s_add_i32 m0, s22, 0x10000
	global_load_lds_dwordx4 v[244:245], off
.Lgc161_nopre:
	v_add_u32_e32 v176, v188, v183
	v_add_u32_e32 v176, 0xffff0000, v176
	v_mfma_f32_32x32x16_bf16 v[96:111], v[226:229], v[172:175], v[96:111]
	v_mfma_f32_32x32x16_bf16 v[48:63], v[226:229], v[164:167], v[48:63]
	v_mfma_f32_32x32x16_bf16 v[32:47], v[226:229], v[210:213], v[32:47]
	v_mfma_f32_32x32x16_bf16 v[80:95], v[222:225], v[214:217], v[80:95]
	v_mfma_f32_32x32x16_bf16 v[64:79], v[222:225], v[172:175], v[64:79]
	v_mfma_f32_32x32x16_bf16 v[16:31], v[222:225], v[164:167], v[16:31]
	v_add_u32_e32 v164, v188, v186
	v_add_u32_e32 v164, 0xffff0000, v164
	v_mfma_f32_32x32x16_bf16 v[0:15], v[222:225], v[210:213], v[0:15]
	v_mfma_f32_32x32x16_bf16 v[112:127], v[160:163], v[152:155], v[112:127]
	v_mfma_f32_32x32x16_bf16 v[96:111], v[160:163], v[144:147], v[96:111]
	v_mfma_f32_32x32x16_bf16 v[48:63], v[160:163], v[140:143], v[48:63]
	v_mfma_f32_32x32x16_bf16 v[32:47], v[160:163], v[148:151], v[32:47]
	v_mfma_f32_32x32x16_bf16 v[80:95], v[156:159], v[152:155], v[80:95]
	ds_read_b128 v[152:155], v128 offset:4096
	ds_read_b128 v[160:163], v128 offset:2048
	v_mfma_f32_32x32x16_bf16 v[64:79], v[156:159], v[144:147], v[64:79]
	ds_read_b128 v[144:147], v128 offset:6144
	ds_read_b128 v[164:167], v164
	v_add_u32_e32 v128, v189, v186
	v_add_u32_e32 v128, 0xffff0000, v128
	ds_read_b128 v[168:171], v128 offset:2048
	ds_read_b128 v[172:175], v128
	v_add_u32_e32 v128, v187, v183
	v_add_u32_e32 v128, 0xffff0000, v128
	v_mfma_f32_32x32x16_bf16 v[16:31], v[156:159], v[140:143], v[16:31]
	ds_read_b128 v[140:143], v128 offset:4096
	ds_read_b128 v[210:213], v128 offset:2048
	ds_read_b128 v[214:217], v128 offset:6144
	ds_read_b128 v[218:221], v176
	v_add_u32_e32 v128, v189, v183
	v_add_u32_e32 v128, 0xffff0000, v128
	ds_read_b128 v[222:225], v128 offset:2048
	ds_read_b128 v[226:229], v128
	v_mfma_f32_32x32x16_bf16 v[0:15], v[156:159], v[148:151], v[0:15]
	s_waitcnt lgkmcnt(0)
	v_mfma_f32_32x32x16_bf16 v[112:127], v[226:229], v[218:221], v[112:127]
	s_waitcnt lgkmcnt(0)
	s_cmp_eq_u32 s94, 6
	s_cselect_b64 s[24:25], -1, 0
	s_cmp_lg_u32 s94, 6
	s_barrier
	s_cselect_b64 s[22:23], -1, 0
	s_mov_b64 s[58:59], -1
	v_mfma_f32_32x32x16_bf16 v[96:111], v[226:229], v[210:213], v[96:111]
	v_mfma_f32_32x32x16_bf16 v[48:63], v[226:229], v[140:143], v[48:63]
	v_mfma_f32_32x32x16_bf16 v[32:47], v[226:229], v[214:217], v[32:47]
	v_mfma_f32_32x32x16_bf16 v[80:95], v[222:225], v[218:221], v[80:95]
	v_mfma_f32_32x32x16_bf16 v[64:79], v[222:225], v[210:213], v[64:79]
	v_mov_b32_e32 v211, v133
	s_nop 0
	v_and_b32_e32 v212, 31, v211
	v_ashrrev_i32_e32 v213, 5, v211
	v_mfma_f32_32x32x16_bf16 v[16:31], v[222:225], v[140:143], v[16:31]
	v_add_u32_e32 v140, s6, v190
	v_or_b32_e32 v142, s93, v132
	v_ashrrev_i32_e32 v210, 14, v140
	v_cmp_lt_i32_e64 s[4:5], s55, v142
	v_mfma_f32_32x32x16_bf16 v[0:15], v[222:225], v[214:217], v[0:15]
	v_mfma_f32_32x32x16_bf16 v[112:127], v[172:175], v[164:167], v[112:127]
	v_mfma_f32_32x32x16_bf16 v[96:111], v[172:175], v[160:163], v[96:111]
	v_mfma_f32_32x32x16_bf16 v[48:63], v[172:175], v[152:155], v[48:63]
	v_mfma_f32_32x32x16_bf16 v[32:47], v[172:175], v[144:147], v[32:47]
	v_mfma_f32_32x32x16_bf16 v[80:95], v[168:171], v[164:167], v[80:95]
	v_mfma_f32_32x32x16_bf16 v[64:79], v[168:171], v[160:163], v[64:79]
	v_mfma_f32_32x32x16_bf16 v[16:31], v[168:171], v[152:155], v[16:31]
	v_mfma_f32_32x32x16_bf16 v[0:15], v[168:171], v[144:147], v[0:15]
	s_and_saveexec_b64 s[48:49], s[4:5]
	s_cbranch_execz .LBB0_197
	s_cmp_lt_i32 s94, 8
	s_cbranch_scc1 .LBB0_165
	s_cmp_lg_u32 s94, 8
	s_mov_b64 s[6:7], -1
	s_cselect_b64 s[58:59], -1, 0
	s_cbranch_execz .LBB0_166
	s_branch .LBB0_167
